# grid barrier: all waiters poll TOP against (gen+1)*nx target instead of TOPGEN (removes last-leader round trip)
# speedup vs baseline: 1.0620x; 1.0123x over previous
; __device__ __forceinline__ unsigned xb_ld(unsigned* p)              { return __hip_atomic_load(p, __ATOMIC_RELAXED, __HIP_MEMORY_SCOPE_AGENT); }
; __device__ __forceinline__ unsigned xb_add(unsigned* p, unsigned v) { return __hip_atomic_fetch_add(p, v, __ATOMIC_RELAXED, __HIP_MEMORY_SCOPE_AGENT); }
; #define XB_SPIN(cond, bar) do { unsigned _sp = 0; while (cond) { __builtin_amdgcn_s_sleep(1); \
;     if ((++_sp & 255u) == 0u) { if (xb_ld(&(bar)[XB_TMO])) break; if (_sp > XB_SPIN_CAP) { atomicAdd(&(bar)[XB_TMO], 1u); break; } } } } while (0)
; __device__ __forceinline__ void xcd_barrier(const XcdBarrier& b, bool leader_thread) {
;     ...
;         unsigned nloc = b.st[0], nx = b.st[1];
;         if (nloc == 0u) { xcd_barrier_complete(bar, b.x, nloc, nx); b.st[0] = nloc; b.st[1] = nx; }
;         const unsigned old = xb_add(&bar[XB_XSUB(b.x)], 1u);
;         const unsigned gen = old / nloc;
;         if (old + 1u == (gen + 1u) * nloc) {
;             __builtin_amdgcn_fence(__ATOMIC_RELEASE, "agent");
;             asm volatile("s_waitcnt vmcnt(0)" ::: "memory");
;             const unsigned og = xb_add(&bar[XB_TOP], 1u);
;             const unsigned tg = og / nx;
;             if (og + 1u == (tg + 1u) * nx) xb_add(&bar[XB_TOPGEN], 1u);
;             else XB_SPIN(xb_ld(&bar[XB_TOPGEN]) == tg, bar);
;             __builtin_amdgcn_fence(__ATOMIC_ACQUIRE, "agent");
;             xb_add(&bar[XB_XGEN(b.x)], 1u);
;             asm volatile("s_waitcnt vmcnt(0)" ::: "memory");
;         } else {
;             XB_SPIN(xb_ld(&bar[XB_XGEN(b.x)]) == gen, bar);
.LBB0_140:
	s_or_b64 exec, exec, s[4:5]
	v_cvt_f32_u32_e32 v5, v3
	s_waitcnt vmcnt(0)
	v_readfirstlane_b32 s2, v4
	v_sub_u32_e32 v4, 0, v3
	v_rcp_iflag_f32_e32 v5, v5
	v_add_u32_e32 v6, s2, v0
	v_mul_f32_e32 v5, 0x4f7ffffe, v5
	v_cvt_u32_f32_e32 v5, v5
	v_mul_lo_u32 v0, v4, v5
	v_mul_hi_u32 v0, v5, v0
	v_add_u32_e32 v0, v5, v0
	v_mul_hi_u32 v0, v6, v0
	v_mul_lo_u32 v4, v0, v3
	v_sub_u32_e32 v4, v6, v4
	v_add_u32_e32 v5, 1, v0
	v_cmp_ge_u32_e32 vcc, v4, v3
	s_nop 1
	v_cndmask_b32_e32 v0, v0, v5, vcc
	v_sub_u32_e32 v5, v4, v3
	v_cndmask_b32_e32 v4, v4, v5, vcc
	v_add_u32_e32 v5, 1, v0
	v_cmp_ge_u32_e32 vcc, v4, v3
	v_add_u32_e32 v4, 1, v6
	s_nop 0
	v_cndmask_b32_e32 v0, v0, v5, vcc
	v_mul_lo_u32 v5, v3, v0
	v_add_u32_e32 v3, v5, v3
	v_cmp_ne_u32_e32 vcc, v4, v3
	s_and_saveexec_b64 s[2:3], vcc
	s_xor_b64 s[4:5], exec, s[2:3]
	s_cbranch_execz .LBB0_154
	v_readlane_b32 s2, v252, 57
	v_readlane_b32 s3, v252, 58
	s_waitcnt lgkmcnt(0)
	v_add_u32_e32 v17, 1, v0
	v_mul_lo_u32 v17, v17, v2
	s_nop 3
	global_load_dword v2, v1, s[2:3] sc1
	s_waitcnt vmcnt(0)
	v_cmp_gt_u32_e32 vcc, v17, v2
	s_and_saveexec_b64 s[6:7], vcc
	s_cbranch_execz .LBB0_153
	s_mov_b32 s2, 1
	s_mov_b64 s[8:9], 0
	s_branch .LBB0_144

; __device__ __forceinline__ unsigned xb_ld(unsigned* p)              { return __hip_atomic_load(p, __ATOMIC_RELAXED, __HIP_MEMORY_SCOPE_AGENT); }
; #define XB_SPIN(cond, bar) do { unsigned _sp = 0; while (cond) { __builtin_amdgcn_s_sleep(1); \
;     if ((++_sp & 255u) == 0u) { if (xb_ld(&(bar)[XB_TMO])) break; if (_sp > XB_SPIN_CAP) { atomicAdd(&(bar)[XB_TMO], 1u); break; } } } } while (0)
; __device__ __forceinline__ void xcd_barrier(const XcdBarrier& b, bool leader_thread) {
;     ...
;             XB_SPIN(xb_ld(&bar[XB_XGEN(b.x)]) == gen, bar);
.LBB0_146:
	v_readlane_b32 s20, v252, 57
	v_readlane_b32 s21, v252, 58
	s_add_i32 s2, s2, 1
	s_mov_b64 s[22:23], -1
	s_nop 2
	global_load_dword v2, v1, s[20:21] sc1
	s_waitcnt vmcnt(0)
	v_cmp_le_u32_e32 vcc, v17, v2
	s_orn2_b64 s[20:21], vcc, exec
	s_branch .LBB0_143

; __device__ __forceinline__ unsigned xb_ld(unsigned* p)              { return __hip_atomic_load(p, __ATOMIC_RELAXED, __HIP_MEMORY_SCOPE_AGENT); }
; __device__ __forceinline__ unsigned xb_add(unsigned* p, unsigned v) { return __hip_atomic_fetch_add(p, v, __ATOMIC_RELAXED, __HIP_MEMORY_SCOPE_AGENT); }
; #define XB_SPIN(cond, bar) do { unsigned _sp = 0; while (cond) { __builtin_amdgcn_s_sleep(1); \
;     if ((++_sp & 255u) == 0u) { if (xb_ld(&(bar)[XB_TMO])) break; if (_sp > XB_SPIN_CAP) { atomicAdd(&(bar)[XB_TMO], 1u); break; } } } } while (0)
; __device__ __forceinline__ void xcd_barrier(const XcdBarrier& b, bool leader_thread) {
;     ...
;             const unsigned og = xb_add(&bar[XB_TOP], 1u);
;             const unsigned tg = og / nx;
;             if (og + 1u == (tg + 1u) * nx) xb_add(&bar[XB_TOPGEN], 1u);
;             else XB_SPIN(xb_ld(&bar[XB_TOPGEN]) == tg, bar);
.LBB0_157:
	s_or_b64 exec, exec, s[6:7]
	v_cvt_f32_u32_e32 v4, v2
	s_waitcnt vmcnt(0)
	v_readfirstlane_b32 s2, v3
	s_mov_b64 s[6:7], -1
	v_rcp_iflag_f32_e32 v4, v4
	v_add_u32_e32 v0, s2, v0
	v_add_u32_e32 v5, 1, v0
	v_readlane_b32 s2, v252, 59
	v_mul_f32_e32 v3, 0x4f7ffffe, v4
	v_cvt_u32_f32_e32 v3, v3
	v_sub_u32_e32 v4, 0, v2
	v_readlane_b32 s3, v252, 60
	v_mul_lo_u32 v4, v4, v3
	v_mul_hi_u32 v4, v3, v4
	v_add_u32_e32 v3, v3, v4
	v_mul_hi_u32 v3, v0, v3
	v_mul_lo_u32 v4, v3, v2
	v_sub_u32_e32 v0, v0, v4
	v_add_u32_e32 v6, 1, v3
	v_cmp_ge_u32_e32 vcc, v0, v2
	v_sub_u32_e32 v4, v0, v2
	s_nop 0
	v_cndmask_b32_e32 v3, v3, v6, vcc
	v_cndmask_b32_e32 v0, v0, v4, vcc
	v_add_u32_e32 v4, 1, v3
	v_cmp_ge_u32_e32 vcc, v0, v2
	s_nop 1
	v_cndmask_b32_e32 v0, v3, v4, vcc
	v_mul_lo_u32 v3, v2, v0
	v_add_u32_e32 v2, v3, v2
	v_cmp_ne_u32_e32 vcc, v5, v2
	v_mov_b32_e32 v17, v2
	v_mov_b64_e32 v[2:3], s[2:3]
	s_and_saveexec_b64 s[4:5], vcc
	s_cbranch_execz .LBB0_169
	v_readlane_b32 s2, v252, 57
	v_readlane_b32 s3, v252, 58
	s_mov_b64 s[8:9], 0
	s_nop 3
	global_load_dword v2, v1, s[2:3] sc1
	s_waitcnt vmcnt(0)
	v_cmp_gt_u32_e32 vcc, v17, v2
	s_and_saveexec_b64 s[6:7], vcc
	s_cbranch_execz .LBB0_168
	s_mov_b32 s2, 1
	s_branch .LBB0_161

; __device__ __forceinline__ unsigned xb_ld(unsigned* p)              { return __hip_atomic_load(p, __ATOMIC_RELAXED, __HIP_MEMORY_SCOPE_AGENT); }
; __device__ __forceinline__ unsigned xb_add(unsigned* p, unsigned v) { return __hip_atomic_fetch_add(p, v, __ATOMIC_RELAXED, __HIP_MEMORY_SCOPE_AGENT); }
; #define XB_SPIN(cond, bar) do { unsigned _sp = 0; while (cond) { __builtin_amdgcn_s_sleep(1); \
;     if ((++_sp & 255u) == 0u) { if (xb_ld(&(bar)[XB_TMO])) break; if (_sp > XB_SPIN_CAP) { atomicAdd(&(bar)[XB_TMO], 1u); break; } } } } while (0)
; __device__ __forceinline__ void xcd_barrier(const XcdBarrier& b, bool leader_thread) {
;     ...
;         unsigned nloc = b.st[0], nx = b.st[1];
;         if (nloc == 0u) { xcd_barrier_complete(bar, b.x, nloc, nx); b.st[0] = nloc; b.st[1] = nx; }
;         const unsigned old = xb_add(&bar[XB_XSUB(b.x)], 1u);
;         const unsigned gen = old / nloc;
;         if (old + 1u == (gen + 1u) * nloc) {
;             __builtin_amdgcn_fence(__ATOMIC_RELEASE, "agent");
;             asm volatile("s_waitcnt vmcnt(0)" ::: "memory");
;             const unsigned og = xb_add(&bar[XB_TOP], 1u);
;             const unsigned tg = og / nx;
;             if (og + 1u == (tg + 1u) * nx) xb_add(&bar[XB_TOPGEN], 1u);
;             else XB_SPIN(xb_ld(&bar[XB_TOPGEN]) == tg, bar);
;             __builtin_amdgcn_fence(__ATOMIC_ACQUIRE, "agent");
;             xb_add(&bar[XB_XGEN(b.x)], 1u);
;             asm volatile("s_waitcnt vmcnt(0)" ::: "memory");
;         } else {
;             XB_SPIN(xb_ld(&bar[XB_XGEN(b.x)]) == gen, bar);
.LBB0_324:
	s_or_b64 exec, exec, s[8:9]
	v_cvt_f32_u32_e32 v5, v3
	s_waitcnt vmcnt(0)
	v_readfirstlane_b32 s3, v4
	v_sub_u32_e32 v4, 0, v3
	v_rcp_iflag_f32_e32 v5, v5
	v_add_u32_e32 v6, s3, v0
	v_mul_f32_e32 v5, 0x4f7ffffe, v5
	v_cvt_u32_f32_e32 v5, v5
	v_mul_lo_u32 v0, v4, v5
	v_mul_hi_u32 v0, v5, v0
	v_add_u32_e32 v0, v5, v0
	v_mul_hi_u32 v0, v6, v0
	v_mul_lo_u32 v4, v0, v3
	v_sub_u32_e32 v4, v6, v4
	v_add_u32_e32 v5, 1, v0
	v_cmp_ge_u32_e32 vcc, v4, v3
	s_nop 1
	v_cndmask_b32_e32 v0, v0, v5, vcc
	v_sub_u32_e32 v5, v4, v3
	v_cndmask_b32_e32 v4, v4, v5, vcc
	v_add_u32_e32 v5, 1, v0
	v_cmp_ge_u32_e32 vcc, v4, v3
	v_add_u32_e32 v4, 1, v6
	s_nop 0
	v_cndmask_b32_e32 v0, v0, v5, vcc
	v_mul_lo_u32 v5, v3, v0
	v_add_u32_e32 v3, v5, v3
	v_cmp_ne_u32_e32 vcc, v4, v3
	s_and_saveexec_b64 s[8:9], vcc
	s_xor_b64 s[8:9], exec, s[8:9]
	s_cbranch_execz .LBB0_338
	v_readlane_b32 s6, v252, 57
	v_readlane_b32 s7, v252, 58
	s_waitcnt lgkmcnt(0)
	v_add_u32_e32 v17, 1, v0
	v_mul_lo_u32 v17, v17, v2
	s_nop 3
	global_load_dword v2, v1, s[6:7] sc1
	s_waitcnt vmcnt(0)
	v_cmp_gt_u32_e32 vcc, v17, v2
	s_and_saveexec_b64 s[10:11], vcc
	s_cbranch_execz .LBB0_337
	s_mov_b32 s3, 1
	s_mov_b64 s[20:21], 0
	s_branch .LBB0_328

; __device__ __forceinline__ unsigned xb_ld(unsigned* p)              { return __hip_atomic_load(p, __ATOMIC_RELAXED, __HIP_MEMORY_SCOPE_AGENT); }
; #define XB_SPIN(cond, bar) do { unsigned _sp = 0; while (cond) { __builtin_amdgcn_s_sleep(1); \
;     if ((++_sp & 255u) == 0u) { if (xb_ld(&(bar)[XB_TMO])) break; if (_sp > XB_SPIN_CAP) { atomicAdd(&(bar)[XB_TMO], 1u); break; } } } } while (0)
; __device__ __forceinline__ void xcd_barrier(const XcdBarrier& b, bool leader_thread) {
;     ...
;             XB_SPIN(xb_ld(&bar[XB_XGEN(b.x)]) == gen, bar);
.LBB0_330:
	v_readlane_b32 s6, v252, 57
	v_readlane_b32 s7, v252, 58
	s_add_i32 s3, s3, 1
	s_mov_b64 s[30:31], -1
	s_nop 2
	global_load_dword v2, v1, s[6:7] sc1
	s_waitcnt vmcnt(0)
	v_cmp_le_u32_e32 vcc, v17, v2
	s_orn2_b64 s[24:25], vcc, exec
	s_branch .LBB0_327

; __device__ __forceinline__ unsigned xb_ld(unsigned* p)              { return __hip_atomic_load(p, __ATOMIC_RELAXED, __HIP_MEMORY_SCOPE_AGENT); }
; __device__ __forceinline__ unsigned xb_add(unsigned* p, unsigned v) { return __hip_atomic_fetch_add(p, v, __ATOMIC_RELAXED, __HIP_MEMORY_SCOPE_AGENT); }
; #define XB_SPIN(cond, bar) do { unsigned _sp = 0; while (cond) { __builtin_amdgcn_s_sleep(1); \
;     if ((++_sp & 255u) == 0u) { if (xb_ld(&(bar)[XB_TMO])) break; if (_sp > XB_SPIN_CAP) { atomicAdd(&(bar)[XB_TMO], 1u); break; } } } } while (0)
; __device__ __forceinline__ void xcd_barrier(const XcdBarrier& b, bool leader_thread) {
;     ...
;             const unsigned og = xb_add(&bar[XB_TOP], 1u);
;             const unsigned tg = og / nx;
;             if (og + 1u == (tg + 1u) * nx) xb_add(&bar[XB_TOPGEN], 1u);
;             else XB_SPIN(xb_ld(&bar[XB_TOPGEN]) == tg, bar);
.LBB0_341:
	s_or_b64 exec, exec, s[10:11]
	s_waitcnt vmcnt(0)
	v_readfirstlane_b32 s3, v3
	v_sub_u32_e32 v4, 0, v2
	v_readlane_b32 s6, v252, 59
	v_add_u32_e32 v3, s3, v0
	v_cvt_f32_u32_e32 v0, v2
	v_readlane_b32 s7, v252, 60
	s_mov_b64 s[10:11], -1
	v_rcp_iflag_f32_e32 v0, v0
	s_nop 0
	v_mul_f32_e32 v0, 0x4f7ffffe, v0
	v_cvt_u32_f32_e32 v0, v0
	v_mul_lo_u32 v4, v4, v0
	v_mul_hi_u32 v4, v0, v4
	v_add_u32_e32 v0, v0, v4
	v_mul_hi_u32 v0, v3, v0
	v_mul_lo_u32 v4, v0, v2
	v_sub_u32_e32 v4, v3, v4
	v_cmp_ge_u32_e32 vcc, v4, v2
	v_add_u32_e32 v5, 1, v0
	v_add_u32_e32 v3, 1, v3
	v_cndmask_b32_e32 v0, v0, v5, vcc
	v_sub_u32_e32 v5, v4, v2
	v_cndmask_b32_e32 v4, v4, v5, vcc
	v_cmp_ge_u32_e32 vcc, v4, v2
	v_add_u32_e32 v4, 1, v0
	s_nop 0
	v_cndmask_b32_e32 v0, v0, v4, vcc
	v_mul_lo_u32 v4, v2, v0
	v_add_u32_e32 v2, v4, v2
	v_cmp_ne_u32_e32 vcc, v3, v2
	v_mov_b32_e32 v17, v2
	v_mov_b64_e32 v[2:3], s[6:7]
	s_and_saveexec_b64 s[8:9], vcc
	s_cbranch_execz .LBB0_353
	v_readlane_b32 s6, v252, 57
	v_readlane_b32 s7, v252, 58
	s_mov_b64 s[20:21], 0
	s_nop 3
	global_load_dword v2, v1, s[6:7] sc1
	s_waitcnt vmcnt(0)
	v_cmp_gt_u32_e32 vcc, v17, v2
	s_and_saveexec_b64 s[10:11], vcc
	s_cbranch_execz .LBB0_352
	s_mov_b32 s3, 1
	s_branch .LBB0_345

; __device__ __forceinline__ unsigned xb_ld(unsigned* p)              { return __hip_atomic_load(p, __ATOMIC_RELAXED, __HIP_MEMORY_SCOPE_AGENT); }
; __device__ __forceinline__ unsigned xb_add(unsigned* p, unsigned v) { return __hip_atomic_fetch_add(p, v, __ATOMIC_RELAXED, __HIP_MEMORY_SCOPE_AGENT); }
; #define XB_SPIN(cond, bar) do { unsigned _sp = 0; while (cond) { __builtin_amdgcn_s_sleep(1); \
;     if ((++_sp & 255u) == 0u) { if (xb_ld(&(bar)[XB_TMO])) break; if (_sp > XB_SPIN_CAP) { atomicAdd(&(bar)[XB_TMO], 1u); break; } } } } while (0)
; __device__ __forceinline__ void xcd_barrier(const XcdBarrier& b, bool leader_thread) {
;     ...
;         unsigned nloc = b.st[0], nx = b.st[1];
;         if (nloc == 0u) { xcd_barrier_complete(bar, b.x, nloc, nx); b.st[0] = nloc; b.st[1] = nx; }
;         const unsigned old = xb_add(&bar[XB_XSUB(b.x)], 1u);
;         const unsigned gen = old / nloc;
;         if (old + 1u == (gen + 1u) * nloc) {
;             __builtin_amdgcn_fence(__ATOMIC_RELEASE, "agent");
;             asm volatile("s_waitcnt vmcnt(0)" ::: "memory");
;             const unsigned og = xb_add(&bar[XB_TOP], 1u);
;             const unsigned tg = og / nx;
;             if (og + 1u == (tg + 1u) * nx) xb_add(&bar[XB_TOPGEN], 1u);
;             else XB_SPIN(xb_ld(&bar[XB_TOPGEN]) == tg, bar);
;             __builtin_amdgcn_fence(__ATOMIC_ACQUIRE, "agent");
;             xb_add(&bar[XB_XGEN(b.x)], 1u);
;             asm volatile("s_waitcnt vmcnt(0)" ::: "memory");
;         } else {
;             XB_SPIN(xb_ld(&bar[XB_XGEN(b.x)]) == gen, bar);
.LBB0_548:
	s_or_b64 exec, exec, s[6:7]
	v_cvt_f32_u32_e32 v5, v3
	s_waitcnt vmcnt(0)
	v_readfirstlane_b32 s3, v4
	v_sub_u32_e32 v4, 0, v3
	v_rcp_iflag_f32_e32 v5, v5
	v_add_u32_e32 v6, s3, v0
	v_mul_f32_e32 v5, 0x4f7ffffe, v5
	v_cvt_u32_f32_e32 v5, v5
	v_mul_lo_u32 v0, v4, v5
	v_mul_hi_u32 v0, v5, v0
	v_add_u32_e32 v0, v5, v0
	v_mul_hi_u32 v0, v6, v0
	v_mul_lo_u32 v4, v0, v3
	v_sub_u32_e32 v4, v6, v4
	v_add_u32_e32 v5, 1, v0
	v_cmp_ge_u32_e32 vcc, v4, v3
	s_nop 1
	v_cndmask_b32_e32 v0, v0, v5, vcc
	v_sub_u32_e32 v5, v4, v3
	v_cndmask_b32_e32 v4, v4, v5, vcc
	v_add_u32_e32 v5, 1, v0
	v_cmp_ge_u32_e32 vcc, v4, v3
	v_add_u32_e32 v4, 1, v6
	s_nop 0
	v_cndmask_b32_e32 v0, v0, v5, vcc
	v_mul_lo_u32 v5, v3, v0
	v_add_u32_e32 v3, v5, v3
	v_cmp_ne_u32_e32 vcc, v4, v3
	s_and_saveexec_b64 s[6:7], vcc
	s_xor_b64 s[6:7], exec, s[6:7]
	s_cbranch_execz .LBB0_562
	v_readlane_b32 s10, v252, 57
	v_readlane_b32 s11, v252, 58
	s_waitcnt lgkmcnt(0)
	v_add_u32_e32 v17, 1, v0
	v_mul_lo_u32 v17, v17, v2
	s_nop 3
	global_load_dword v2, v1, s[10:11] sc1
	s_waitcnt vmcnt(0)
	v_cmp_gt_u32_e32 vcc, v17, v2
	s_and_saveexec_b64 s[10:11], vcc
	s_cbranch_execz .LBB0_561
	s_mov_b32 s3, 1
	s_mov_b64 s[20:21], 0
	s_branch .LBB0_552

; __device__ __forceinline__ unsigned xb_ld(unsigned* p)              { return __hip_atomic_load(p, __ATOMIC_RELAXED, __HIP_MEMORY_SCOPE_AGENT); }
; #define XB_SPIN(cond, bar) do { unsigned _sp = 0; while (cond) { __builtin_amdgcn_s_sleep(1); \
;     if ((++_sp & 255u) == 0u) { if (xb_ld(&(bar)[XB_TMO])) break; if (_sp > XB_SPIN_CAP) { atomicAdd(&(bar)[XB_TMO], 1u); break; } } } } while (0)
; __device__ __forceinline__ void xcd_barrier(const XcdBarrier& b, bool leader_thread) {
;     ...
;             XB_SPIN(xb_ld(&bar[XB_XGEN(b.x)]) == gen, bar);
.LBB0_554:
	v_readlane_b32 s24, v252, 57
	v_readlane_b32 s25, v252, 58
	s_add_i32 s3, s3, 1
	s_mov_b64 s[28:29], -1
	s_nop 2
	global_load_dword v2, v1, s[24:25] sc1
	s_waitcnt vmcnt(0)
	v_cmp_le_u32_e32 vcc, v17, v2
	s_orn2_b64 s[24:25], vcc, exec
	s_branch .LBB0_551

; __device__ __forceinline__ unsigned xb_ld(unsigned* p)              { return __hip_atomic_load(p, __ATOMIC_RELAXED, __HIP_MEMORY_SCOPE_AGENT); }
; __device__ __forceinline__ unsigned xb_add(unsigned* p, unsigned v) { return __hip_atomic_fetch_add(p, v, __ATOMIC_RELAXED, __HIP_MEMORY_SCOPE_AGENT); }
; #define XB_SPIN(cond, bar) do { unsigned _sp = 0; while (cond) { __builtin_amdgcn_s_sleep(1); \
;     if ((++_sp & 255u) == 0u) { if (xb_ld(&(bar)[XB_TMO])) break; if (_sp > XB_SPIN_CAP) { atomicAdd(&(bar)[XB_TMO], 1u); break; } } } } while (0)
; __device__ __forceinline__ void xcd_barrier(const XcdBarrier& b, bool leader_thread) {
;     ...
;             const unsigned og = xb_add(&bar[XB_TOP], 1u);
;             const unsigned tg = og / nx;
;             if (og + 1u == (tg + 1u) * nx) xb_add(&bar[XB_TOPGEN], 1u);
;             else XB_SPIN(xb_ld(&bar[XB_TOPGEN]) == tg, bar);
.LBB0_565:
	s_or_b64 exec, exec, s[10:11]
	s_waitcnt vmcnt(0)
	v_readfirstlane_b32 s3, v3
	v_sub_u32_e32 v4, 0, v2
	v_readlane_b32 s6, v252, 59
	v_add_u32_e32 v3, s3, v0
	v_cvt_f32_u32_e32 v0, v2
	v_readlane_b32 s7, v252, 60
	s_mov_b64 s[10:11], -1
	v_rcp_iflag_f32_e32 v0, v0
	s_nop 0
	v_mul_f32_e32 v0, 0x4f7ffffe, v0
	v_cvt_u32_f32_e32 v0, v0
	v_mul_lo_u32 v4, v4, v0
	v_mul_hi_u32 v4, v0, v4
	v_add_u32_e32 v0, v0, v4
	v_mul_hi_u32 v0, v3, v0
	v_mul_lo_u32 v4, v0, v2
	v_sub_u32_e32 v4, v3, v4
	v_cmp_ge_u32_e32 vcc, v4, v2
	v_add_u32_e32 v5, 1, v0
	v_add_u32_e32 v3, 1, v3
	v_cndmask_b32_e32 v0, v0, v5, vcc
	v_sub_u32_e32 v5, v4, v2
	v_cndmask_b32_e32 v4, v4, v5, vcc
	v_cmp_ge_u32_e32 vcc, v4, v2
	v_add_u32_e32 v4, 1, v0
	s_nop 0
	v_cndmask_b32_e32 v0, v0, v4, vcc
	v_mul_lo_u32 v4, v2, v0
	v_add_u32_e32 v2, v4, v2
	v_cmp_ne_u32_e32 vcc, v3, v2
	v_mov_b32_e32 v17, v2
	v_mov_b64_e32 v[2:3], s[6:7]
	s_and_saveexec_b64 s[6:7], vcc
	s_cbranch_execz .LBB0_577
	v_readlane_b32 s10, v252, 57
	v_readlane_b32 s11, v252, 58
	s_mov_b64 s[20:21], 0
	s_nop 3
	global_load_dword v2, v1, s[10:11] sc1
	s_waitcnt vmcnt(0)
	v_cmp_gt_u32_e32 vcc, v17, v2
	s_and_saveexec_b64 s[10:11], vcc
	s_cbranch_execz .LBB0_576
	s_mov_b32 s3, 1
	s_branch .LBB0_569

; __device__ __forceinline__ unsigned xb_ld(unsigned* p)              { return __hip_atomic_load(p, __ATOMIC_RELAXED, __HIP_MEMORY_SCOPE_AGENT); }
; __device__ __forceinline__ unsigned xb_add(unsigned* p, unsigned v) { return __hip_atomic_fetch_add(p, v, __ATOMIC_RELAXED, __HIP_MEMORY_SCOPE_AGENT); }
; #define XB_SPIN(cond, bar) do { unsigned _sp = 0; while (cond) { __builtin_amdgcn_s_sleep(1); \
;     if ((++_sp & 255u) == 0u) { if (xb_ld(&(bar)[XB_TMO])) break; if (_sp > XB_SPIN_CAP) { atomicAdd(&(bar)[XB_TMO], 1u); break; } } } } while (0)
; __device__ __forceinline__ void xcd_barrier(const XcdBarrier& b, bool leader_thread) {
;     ...
;         unsigned nloc = b.st[0], nx = b.st[1];
;         if (nloc == 0u) { xcd_barrier_complete(bar, b.x, nloc, nx); b.st[0] = nloc; b.st[1] = nx; }
;         const unsigned old = xb_add(&bar[XB_XSUB(b.x)], 1u);
;         const unsigned gen = old / nloc;
;         if (old + 1u == (gen + 1u) * nloc) {
;             __builtin_amdgcn_fence(__ATOMIC_RELEASE, "agent");
;             asm volatile("s_waitcnt vmcnt(0)" ::: "memory");
;             const unsigned og = xb_add(&bar[XB_TOP], 1u);
;             const unsigned tg = og / nx;
;             if (og + 1u == (tg + 1u) * nx) xb_add(&bar[XB_TOPGEN], 1u);
;             else XB_SPIN(xb_ld(&bar[XB_TOPGEN]) == tg, bar);
;             __builtin_amdgcn_fence(__ATOMIC_ACQUIRE, "agent");
;             xb_add(&bar[XB_XGEN(b.x)], 1u);
;             asm volatile("s_waitcnt vmcnt(0)" ::: "memory");
;         } else {
;             XB_SPIN(xb_ld(&bar[XB_XGEN(b.x)]) == gen, bar);
.LBB0_763:
	s_or_b64 exec, exec, s[6:7]
	v_cvt_f32_u32_e32 v5, v3
	s_waitcnt vmcnt(0)
	v_readfirstlane_b32 s3, v4
	v_sub_u32_e32 v4, 0, v3
	v_rcp_iflag_f32_e32 v5, v5
	v_add_u32_e32 v6, s3, v0
	v_mul_f32_e32 v5, 0x4f7ffffe, v5
	v_cvt_u32_f32_e32 v5, v5
	v_mul_lo_u32 v0, v4, v5
	v_mul_hi_u32 v0, v5, v0
	v_add_u32_e32 v0, v5, v0
	v_mul_hi_u32 v0, v6, v0
	v_mul_lo_u32 v4, v0, v3
	v_sub_u32_e32 v4, v6, v4
	v_add_u32_e32 v5, 1, v0
	v_cmp_ge_u32_e32 vcc, v4, v3
	s_nop 1
	v_cndmask_b32_e32 v0, v0, v5, vcc
	v_sub_u32_e32 v5, v4, v3
	v_cndmask_b32_e32 v4, v4, v5, vcc
	v_add_u32_e32 v5, 1, v0
	v_cmp_ge_u32_e32 vcc, v4, v3
	v_add_u32_e32 v4, 1, v6
	s_nop 0
	v_cndmask_b32_e32 v0, v0, v5, vcc
	v_mul_lo_u32 v5, v3, v0
	v_add_u32_e32 v3, v5, v3
	v_cmp_ne_u32_e32 vcc, v4, v3
	s_and_saveexec_b64 s[6:7], vcc
	s_xor_b64 s[6:7], exec, s[6:7]
	s_cbranch_execz .LBB0_777
	v_readlane_b32 s8, v252, 57
	v_readlane_b32 s9, v252, 58
	s_waitcnt lgkmcnt(0)
	v_add_u32_e32 v17, 1, v0
	v_mul_lo_u32 v17, v17, v2
	s_nop 3
	global_load_dword v2, v1, s[8:9] sc1
	s_waitcnt vmcnt(0)
	v_cmp_gt_u32_e32 vcc, v17, v2
	s_and_saveexec_b64 s[8:9], vcc
	s_cbranch_execz .LBB0_776
	s_mov_b32 s3, 1
	s_mov_b64 s[10:11], 0
	s_branch .LBB0_767

; __device__ __forceinline__ unsigned xb_ld(unsigned* p)              { return __hip_atomic_load(p, __ATOMIC_RELAXED, __HIP_MEMORY_SCOPE_AGENT); }
; #define XB_SPIN(cond, bar) do { unsigned _sp = 0; while (cond) { __builtin_amdgcn_s_sleep(1); \
;     if ((++_sp & 255u) == 0u) { if (xb_ld(&(bar)[XB_TMO])) break; if (_sp > XB_SPIN_CAP) { atomicAdd(&(bar)[XB_TMO], 1u); break; } } } } while (0)
; __device__ __forceinline__ void xcd_barrier(const XcdBarrier& b, bool leader_thread) {
;     ...
;             XB_SPIN(xb_ld(&bar[XB_XGEN(b.x)]) == gen, bar);
.LBB0_769:
	v_readlane_b32 s22, v252, 57
	v_readlane_b32 s23, v252, 58
	s_add_i32 s3, s3, 1
	s_mov_b64 s[24:25], -1
	s_nop 2
	global_load_dword v2, v1, s[22:23] sc1
	s_waitcnt vmcnt(0)
	v_cmp_le_u32_e32 vcc, v17, v2
	s_orn2_b64 s[22:23], vcc, exec
	s_branch .LBB0_766

; __device__ __forceinline__ unsigned xb_ld(unsigned* p)              { return __hip_atomic_load(p, __ATOMIC_RELAXED, __HIP_MEMORY_SCOPE_AGENT); }
; __device__ __forceinline__ unsigned xb_add(unsigned* p, unsigned v) { return __hip_atomic_fetch_add(p, v, __ATOMIC_RELAXED, __HIP_MEMORY_SCOPE_AGENT); }
; #define XB_SPIN(cond, bar) do { unsigned _sp = 0; while (cond) { __builtin_amdgcn_s_sleep(1); \
;     if ((++_sp & 255u) == 0u) { if (xb_ld(&(bar)[XB_TMO])) break; if (_sp > XB_SPIN_CAP) { atomicAdd(&(bar)[XB_TMO], 1u); break; } } } } while (0)
; __device__ __forceinline__ void xcd_barrier(const XcdBarrier& b, bool leader_thread) {
;     ...
;             const unsigned og = xb_add(&bar[XB_TOP], 1u);
;             const unsigned tg = og / nx;
;             if (og + 1u == (tg + 1u) * nx) xb_add(&bar[XB_TOPGEN], 1u);
;             else XB_SPIN(xb_ld(&bar[XB_TOPGEN]) == tg, bar);
.LBB0_780:
	s_or_b64 exec, exec, s[8:9]
	s_waitcnt vmcnt(0)
	v_readfirstlane_b32 s3, v3
	v_sub_u32_e32 v4, 0, v2
	v_readlane_b32 s6, v252, 59
	v_add_u32_e32 v3, s3, v0
	v_cvt_f32_u32_e32 v0, v2
	v_readlane_b32 s7, v252, 60
	s_mov_b64 s[8:9], -1
	v_rcp_iflag_f32_e32 v0, v0
	s_nop 0
	v_mul_f32_e32 v0, 0x4f7ffffe, v0
	v_cvt_u32_f32_e32 v0, v0
	v_mul_lo_u32 v4, v4, v0
	v_mul_hi_u32 v4, v0, v4
	v_add_u32_e32 v0, v0, v4
	v_mul_hi_u32 v0, v3, v0
	v_mul_lo_u32 v4, v0, v2
	v_sub_u32_e32 v4, v3, v4
	v_cmp_ge_u32_e32 vcc, v4, v2
	v_add_u32_e32 v5, 1, v0
	v_add_u32_e32 v3, 1, v3
	v_cndmask_b32_e32 v0, v0, v5, vcc
	v_sub_u32_e32 v5, v4, v2
	v_cndmask_b32_e32 v4, v4, v5, vcc
	v_cmp_ge_u32_e32 vcc, v4, v2
	v_add_u32_e32 v4, 1, v0
	s_nop 0
	v_cndmask_b32_e32 v0, v0, v4, vcc
	v_mul_lo_u32 v4, v2, v0
	v_add_u32_e32 v2, v4, v2
	v_cmp_ne_u32_e32 vcc, v3, v2
	v_mov_b32_e32 v17, v2
	v_mov_b64_e32 v[2:3], s[6:7]
	s_and_saveexec_b64 s[6:7], vcc
	s_cbranch_execz .LBB0_792
	v_readlane_b32 s8, v252, 57
	v_readlane_b32 s9, v252, 58
	s_mov_b64 s[10:11], 0
	s_nop 3
	global_load_dword v2, v1, s[8:9] sc1
	s_waitcnt vmcnt(0)
	v_cmp_gt_u32_e32 vcc, v17, v2
	s_and_saveexec_b64 s[8:9], vcc
	s_cbranch_execz .LBB0_791
	s_mov_b32 s3, 1
	s_branch .LBB0_784

; __device__ __forceinline__ unsigned xb_ld(unsigned* p)              { return __hip_atomic_load(p, __ATOMIC_RELAXED, __HIP_MEMORY_SCOPE_AGENT); }
; __device__ __forceinline__ unsigned xb_add(unsigned* p, unsigned v) { return __hip_atomic_fetch_add(p, v, __ATOMIC_RELAXED, __HIP_MEMORY_SCOPE_AGENT); }
; #define XB_SPIN(cond, bar) do { unsigned _sp = 0; while (cond) { __builtin_amdgcn_s_sleep(1); \
;     if ((++_sp & 255u) == 0u) { if (xb_ld(&(bar)[XB_TMO])) break; if (_sp > XB_SPIN_CAP) { atomicAdd(&(bar)[XB_TMO], 1u); break; } } } } while (0)
; __device__ __forceinline__ void xcd_barrier(const XcdBarrier& b, bool leader_thread) {
;     ...
;             const unsigned og = xb_add(&bar[XB_TOP], 1u);
;             const unsigned tg = og / nx;
;             if (og + 1u == (tg + 1u) * nx) xb_add(&bar[XB_TOPGEN], 1u);
;             else XB_SPIN(xb_ld(&bar[XB_TOPGEN]) == tg, bar);
.LBB0_1301:
	s_or_b64 exec, exec, s[6:7]
	s_waitcnt vmcnt(0)
	v_readfirstlane_b32 s2, v3
	v_sub_u32_e32 v4, 0, v2
	s_mov_b64 s[6:7], -1
	v_add_u32_e32 v3, s2, v0
	v_cvt_f32_u32_e32 v0, v2
	v_readlane_b32 s2, v252, 59
	v_readlane_b32 s3, v252, 60
	v_rcp_iflag_f32_e32 v0, v0
	s_nop 0
	v_mul_f32_e32 v0, 0x4f7ffffe, v0
	v_cvt_u32_f32_e32 v0, v0
	v_mul_lo_u32 v4, v4, v0
	v_mul_hi_u32 v4, v0, v4
	v_add_u32_e32 v0, v0, v4
	v_mul_hi_u32 v0, v3, v0
	v_mul_lo_u32 v4, v0, v2
	v_sub_u32_e32 v4, v3, v4
	v_cmp_ge_u32_e32 vcc, v4, v2
	v_add_u32_e32 v5, 1, v0
	v_add_u32_e32 v3, 1, v3
	v_cndmask_b32_e32 v0, v0, v5, vcc
	v_sub_u32_e32 v5, v4, v2
	v_cndmask_b32_e32 v4, v4, v5, vcc
	v_cmp_ge_u32_e32 vcc, v4, v2
	v_add_u32_e32 v4, 1, v0
	s_nop 0
	v_cndmask_b32_e32 v0, v0, v4, vcc
	v_mul_lo_u32 v4, v2, v0
	v_add_u32_e32 v2, v4, v2
	v_cmp_ne_u32_e32 vcc, v3, v2
	v_mov_b32_e32 v17, v2
	v_mov_b64_e32 v[2:3], s[2:3]
	s_and_saveexec_b64 s[4:5], vcc
	s_cbranch_execz .LBB0_1313
	v_readlane_b32 s2, v252, 57
	v_readlane_b32 s3, v252, 58
	s_mov_b64 s[8:9], 0
	s_nop 3
	global_load_dword v2, v1, s[2:3] sc1
	s_waitcnt vmcnt(0)
	v_cmp_gt_u32_e32 vcc, v17, v2
	s_and_saveexec_b64 s[6:7], vcc
	s_cbranch_execz .LBB0_1312
	s_mov_b32 s2, 1
	s_branch .LBB0_1305
